# prologue: mod GEMV items remapped so a workgroup reads 8 adjacent column groups per weight row, and the w_s / pool_w conversion loads issued before the GEMV
# speedup vs baseline: 1.0229x; 1.0001x over previous
.LBB0_23:
	s_or_b64 exec, exec, s[4:5]
	s_ashr_i32 s22, s8, 6
	s_lshl_b32 s90, s91, 3
	s_lshl_b32 s18, s94, 3
	s_add_i32 s19, s22, s90
	s_add_u32 s92, s34, 0x10000
	s_addc_u32 s93, s35, 0
	s_waitcnt vmcnt(3)
	v_and_b32_e32 v16, 63, v1
	s_cmpk_gt_i32 s19, 0xbff
	s_waitcnt lgkmcnt(0)
	s_barrier
	s_cbranch_scc1 .LBB0_30
	s_cmpk_lg_i32 s94, 0x100
	s_cbranch_scc1 p0b_noearly
	s_load_dwordx2 s[6:7], s[0:1], 0x60
	s_load_dwordx2 s[8:9], s[0:1], 0x70
	v_lshl_add_u32 v240, s91, 9, v1
	v_lshlrev_b32_e32 v241, 2, v240
	v_and_b32_e32 v244, 0x7fff, v240
	v_lshrrev_b32_e32 v245, 12, v244
	v_lshlrev_b32_e32 v246, 6, v244
	v_lshrrev_b32_e32 v247, 4, v244
	v_lshlrev_b32_e32 v245, 14, v245
	v_and_b32_e32 v246, 0xfc0, v246
	v_and_b32_e32 v247, 0xfc, v247
	v_lshl_add_u32 v245, v246, 2, v245
	v_add_u32_e32 v245, v245, v247
	s_waitcnt lgkmcnt(0)
	global_load_dword v242, v241, s[6:7]
	global_load_dword v243, v245, s[8:9]
p0b_noearly:
	s_movk_i32 s6, 0x6000
	s_mov_b32 s7, 0xc000
	s_mov_b32 s8, 0x12000
	s_mov_b32 s9, 0x18000
	s_mov_b32 s10, 0x1e000
	s_mov_b32 s11, 0x24000
	s_mov_b32 s14, 0x2a000
	s_mov_b32 s15, 0x30000
	s_mov_b32 s23, 0x36000
	s_mov_b32 s33, 0x3c000
	s_mov_b32 s36, 0x42000
	s_mov_b32 s37, 0x48000
	s_mov_b32 s38, 0x4e000
	s_mov_b32 s39, 0x54000
	s_mov_b32 s40, 0x5a000
	v_mov_b32_e32 v17, 0x36000
	s_mov_b32 s41, s19
	s_mov_b32 s98, 0
	s_mov_b32 s99, 0x180000
	s_mov_b32 s100, 0
	s_cmpk_eq_i32 s18, 0x800
	s_cselect_b32 s101, 1, 0
	s_branch .LBB0_26

.LBB0_26:
	s_mul_hi_i32 s5, s41, 0x2aaaaaab
	s_lshr_b32 s13, s5, 31
	s_ashr_i32 s5, s5, 8
	s_add_i32 s42, s5, s13
	s_lshr_b32 s12, s41, 3
	s_and_b32 s12, s12, 15
	s_lshr_b32 s4, s41, 7
	s_mul_i32 s5, s42, 12
	s_sub_i32 s4, s4, s5
	s_lshl_b32 s4, s4, 3
	s_and_b32 s5, s41, 7
	s_add_i32 s4, s4, s5
	s_waitcnt vmcnt(0)
	v_lshl_or_b32 v2, s4, 6, v16
	s_mul_i32 s4, s12, 0x60000
	s_mul_i32 s43, s42, 0x1800000
	s_ashr_i32 s5, s4, 31
	s_mul_hi_i32 s13, s42, 0x1800000
	s_add_u32 s43, s24, s43
	s_addc_u32 s13, s25, s13
	s_lshl_b64 s[4:5], s[4:5], 2
	s_add_u32 s4, s43, s4
	v_ashrrev_i32_e32 v3, 31, v2
	s_addc_u32 s5, s13, s5
	v_lshl_add_u64 v[8:9], v[2:3], 2, s[4:5]
	s_lshl_b32 s4, s12, 8
	s_cmp_lg_u32 s100, 0
	s_cselect_b32 s5, 0x80, 0
	v_mov_b32_e32 v12, 0
	s_add_i32 s13, s4, s5
	s_mov_b32 s4, s100
	s_mov_b32 s5, 0
	v_mov_b32_e32 v13, v12
	v_mov_b32_e32 v10, v12
	v_mov_b32_e32 v11, v12
	v_mov_b32_e32 v6, v12
	v_mov_b32_e32 v7, v12
	v_mov_b32_e32 v4, v12
	v_mov_b32_e32 v5, v12
	v_mov_b32_e32 v18, v12

.LBB0_33:
	s_or_b64 exec, exec, s[8:9]
	s_cmpk_lg_i32 s94, 0x100
	s_cbranch_scc1 p0b_orig
	s_load_dwordx16 s[36:51], s[0:1], 0x40
	s_add_u32 s96, s34, 0x180000
	s_addc_u32 s97, s35, 0
	s_add_u32 s68, s34, 0x1c0000
	s_addc_u32 s69, s35, 0
	s_movk_i32 s10, 0x7fff
	v_bfe_u32 v3, v242, 16, 1
	v_bfe_u32 v4, v243, 16, 1
	v_lshlrev_b32_e32 v5, 1, v240
	v_add3_u32 v3, v242, v3, s10
	v_add3_u32 v4, v243, v4, s10
	v_cmp_gt_u32_e32 vcc, 0x8000, v240
	global_store_short_d16_hi v5, v3, s[96:97]
	s_and_saveexec_b64 s[4:5], vcc
	global_store_short_d16_hi v5, v4, s[68:69]
	s_waitcnt lgkmcnt(0)
	s_branch .LBB0_49
p0b_orig:
	v_cvt_f32_u32_e32 v3, s6
	s_load_dwordx16 s[36:51], s[0:1], 0x40
	s_add_u32 s96, s34, 0x180000
	s_mov_b32 s0, 0x20000
	v_rcp_iflag_f32_e32 v10, v3
	s_addc_u32 s97, s35, 0
	v_cmp_gt_i32_e32 vcc, s0, v2
	v_add_u32_e32 v3, s6, v2
	s_and_saveexec_b64 s[4:5], vcc
	s_cbranch_execz .LBB0_41
	v_mul_f32_e32 v6, 0x4f7ffffe, v10
	v_cvt_u32_f32_e32 v6, v6
	v_mov_b32_e32 v5, s6
	v_cmp_gt_i32_e32 vcc, s0, v3
	v_max_i32_e32 v4, 0x20000, v3
	s_mov_b64 s[8:9], -1
	v_addc_co_u32_e64 v5, s[0:1], v2, v5, vcc
	s_sub_i32 s0, 0, s6
	v_sub_u32_e32 v4, v4, v5
	v_mul_lo_u32 v5, s0, v6
	v_mul_hi_u32 v5, v6, v5
	v_add_u32_e32 v5, v6, v5
	v_mul_hi_u32 v5, v4, v5
	v_mul_lo_u32 v6, v5, s6
	v_sub_u32_e32 v4, v4, v6
	v_add_u32_e32 v6, 1, v5
	v_cmp_le_u32_e64 s[0:1], s6, v4
	s_nop 1
	v_cndmask_b32_e64 v5, v5, v6, s[0:1]
	v_subrev_u32_e32 v6, s6, v4
	v_cndmask_b32_e64 v4, v4, v6, s[0:1]
	v_add_u32_e32 v6, 1, v5
	v_cmp_le_u32_e64 s[0:1], s6, v4
	s_nop 1
	v_cndmask_b32_e64 v4, v5, v6, s[0:1]
	v_addc_co_u32_e32 v6, vcc, 1, v4, vcc
	v_cmp_lt_u32_e32 vcc, 1, v6
	v_mov_b32_e32 v4, v2
	s_and_saveexec_b64 s[0:1], vcc
	s_cbranch_execz .LBB0_38
	v_and_b32_e32 v7, -2, v6
	s_lshl_b32 s7, s94, 10
	s_mov_b32 s10, s7
	s_mov_b64 s[8:9], 0
	s_movk_i32 s11, 0x7fff
	v_mov_b32_e32 v8, 1
	v_mov_b32_e32 v9, v7
	v_mov_b64_e32 v[4:5], v[2:3]
